# attention K/V staging: second group of row loads issued with the first group into v240-255
# baseline (speedup 1.0000x reference)
; #define LAS __attribute__((address_space(3)))
; __device__ __forceinline__ unsigned pk2(float lo, float hi) { return f2bf(lo) | (f2bf(hi) << 16); }
; __device__ __forceinline__ void attn_item(Frame& F, int item) {
;     ...
;         float ss = 0.f;
; #pragma unroll
;         for (int i = 0; i < 4; ++i)
; #pragma unroll
;             for (int j = 0; j < 4; ++j) { const float a = bflo(kw[i][j]), c = bfhi(kw[i][j]); ss += a * a + c * c; }
;         ss += __shfl_xor(ss, 1);
;         const float rs = __builtin_amdgcn_rsqf(ss * (1.0f / 64.0f) + EPS);
; #pragma unroll
;         for (int i = 0; i < 4; ++i) {
;             const f32x4 g0 = *(const f32x4*)(F.kg + half * 32 + 8 * i), g1 = *(const f32x4*)(F.kg + half * 32 + 8 * i + 4);
;             v4u o;
;             o.x = pk2(bflo(kw[i][0]) * rs * g0[0], bfhi(kw[i][0]) * rs * g0[1]); o.y = pk2(bflo(kw[i][1]) * rs * g0[2], bfhi(kw[i][1]) * rs * g0[3]);
;             o.z = pk2(bflo(kw[i][2]) * rs * g1[0], bfhi(kw[i][2]) * rs * g1[1]); o.w = pk2(bflo(kw[i][3]) * rs * g1[2], bfhi(kw[i][3]) * rs * g1[3]);
;             *(LAS v4u*)(Ks + key * KS_STRIDE + half * 32 + 8 * i) = o;
; #pragma unroll
;             for (int j = 0; j < 4; ++j) {
;                 Vt[(half * 32 + 8 * i + 2 * j) * VT2_STRIDE + key] = (bf16)(vw[i][j] & 0xffffu);
;                 Vt[(half * 32 + 8 * i + 2 * j + 1) * VT2_STRIDE + key] = (bf16)(vw[i][j] >> 16);
;             }
;         }
.LBB0_488:
	s_or_b64 exec, exec, s[78:79]
	global_load_dwordx4 v[56:59], v[194:195], off
	global_load_dwordx4 v[60:63], v[194:195], off offset:16
	global_load_dwordx4 v[22:25], v[194:195], off offset:48
	global_load_dwordx4 v[26:29], v[194:195], off offset:32
	global_load_dwordx4 v[240:243], v[194:195], off offset:80
	global_load_dwordx4 v[244:247], v[194:195], off offset:64
	global_load_dwordx4 v[248:251], v[194:195], off offset:112
	global_load_dwordx4 v[252:255], v[194:195], off offset:96
	s_waitcnt vmcnt(14)
	v_lshlrev_b32_e32 v55, 16, v39
	v_lshlrev_b32_e32 v54, 16, v38
	v_and_b32_e32 v53, 0xffff0000, v39
	v_and_b32_e32 v52, 0xffff0000, v38
	v_lshlrev_b32_e32 v51, 16, v41
	v_lshlrev_b32_e32 v50, 16, v40
	v_and_b32_e32 v49, 0xffff0000, v41
	v_and_b32_e32 v48, 0xffff0000, v40
	s_waitcnt vmcnt(11)
	v_lshlrev_b32_e32 v41, 16, v45
	v_lshlrev_b32_e32 v40, 16, v44
	v_and_b32_e32 v39, 0xffff0000, v45
	v_and_b32_e32 v38, 0xffff0000, v44
	v_lshlrev_b32_e32 v45, 16, v35
	v_lshlrev_b32_e32 v44, 16, v34
	v_and_b32_e32 v35, 0xffff0000, v35
	v_and_b32_e32 v34, 0xffff0000, v34
	v_lshlrev_b32_e32 v65, 16, v37
	v_lshlrev_b32_e32 v64, 16, v36
	v_and_b32_e32 v37, 0xffff0000, v37
	v_and_b32_e32 v36, 0xffff0000, v36
	v_pk_mul_f32 v[78:79], v[34:35], v[34:35]
	v_pk_mul_f32 v[80:81], v[36:37], v[36:37]
	v_pk_fma_f32 v[78:79], v[44:45], v[44:45], v[78:79]
	v_and_b32_e32 v69, 0xffff0000, v31
	v_and_b32_e32 v68, 0xffff0000, v30
	v_pk_fma_f32 v[80:81], v[64:65], v[64:65], v[80:81]
	v_add_f32_e32 v1, v78, v79
	v_lshlrev_b32_e32 v67, 16, v31
	v_lshlrev_b32_e32 v66, 16, v30
	v_pk_mul_f32 v[82:83], v[68:69], v[68:69]
	v_add_f32_e32 v1, v80, v1
	s_waitcnt vmcnt(8)
	v_and_b32_e32 v73, 0xffff0000, v33
	v_and_b32_e32 v72, 0xffff0000, v32
	v_pk_fma_f32 v[82:83], v[66:67], v[66:67], v[82:83]
	v_add_f32_e32 v1, v81, v1
	v_lshlrev_b32_e32 v71, 16, v33
	v_lshlrev_b32_e32 v70, 16, v32
	v_pk_mul_f32 v[84:85], v[72:73], v[72:73]
	v_add_f32_e32 v1, v82, v1
	v_pk_fma_f32 v[84:85], v[70:71], v[70:71], v[84:85]
	v_add_f32_e32 v1, v83, v1
	v_pk_mul_f32 v[30:31], v[52:53], v[52:53]
	v_add_f32_e32 v1, v84, v1
	v_pk_fma_f32 v[30:31], v[54:55], v[54:55], v[30:31]
	v_add_f32_e32 v1, v85, v1
	v_pk_mul_f32 v[32:33], v[48:49], v[48:49]
	v_add_f32_e32 v1, v30, v1
	v_lshlrev_b32_e32 v47, 16, v43
	v_lshlrev_b32_e32 v46, 16, v42
	v_and_b32_e32 v43, 0xffff0000, v43
	v_and_b32_e32 v42, 0xffff0000, v42
	v_pk_fma_f32 v[32:33], v[50:51], v[50:51], v[32:33]
	v_add_f32_e32 v1, v31, v1
	v_pk_mul_f32 v[74:75], v[42:43], v[42:43]
	v_add_f32_e32 v1, v32, v1
	v_pk_fma_f32 v[74:75], v[46:47], v[46:47], v[74:75]
	v_add_f32_e32 v1, v33, v1
	v_pk_mul_f32 v[76:77], v[38:39], v[38:39]
	v_add_f32_e32 v1, v74, v1
	v_pk_fma_f32 v[76:77], v[40:41], v[40:41], v[76:77]
	v_add_f32_e32 v1, v75, v1
	v_add_f32_e32 v1, v76, v1
	v_add_f32_e32 v1, v77, v1
	ds_bpermute_b32 v5, v187, v1
	s_and_b32 s0, s81, 1
	s_lshl_b32 s78, s0, 4
	s_add_u32 s78, s50, s78
	s_addc_u32 s79, s51, 0
	s_waitcnt lgkmcnt(0)
	v_add_f32_e32 v1, v1, v5
	v_fmamk_f32 v1, v1, 0x3c800000, v213
	s_and_b32 s81, s84, 15
	s_lshl_b32 s0, s0, 9
	s_cmp_eq_u32 s80, 0
	v_lshl_or_b32 v158, s81, 7, v209
	s_cselect_b64 s[80:81], -1, 0
	s_add_u32 s82, s33, s82
	v_mov_b32_e32 v159, v4
	s_waitcnt vmcnt(7)
	v_mov_b32_e32 v30, v56
	s_waitcnt vmcnt(6)
	v_mov_b32_e32 v32, v60
	v_rsq_f32_e32 v60, v1
	v_mov_b32_e32 v31, v58
	s_waitcnt vmcnt(4)
	v_mov_b32_e32 v74, v26
	v_mov_b32_e32 v75, v28
	v_mov_b32_e32 v28, v27
	v_pk_mul_f32 v[26:27], v[60:61], v[44:45] op_sel_hi:[0,1]
	v_mov_b32_e32 v58, v57
	v_pk_mul_f32 v[26:27], v[30:31], v[26:27]
	v_pk_mul_f32 v[30:31], v[60:61], v[34:35] op_sel_hi:[0,1]
	v_mov_b32_e32 v33, v62
	v_pk_mul_f32 v[44:45], v[58:59], v[30:31]
	v_pk_mul_f32 v[30:31], v[60:61], v[64:65] op_sel_hi:[0,1]
	v_mov_b32_e32 v62, v61
	v_pk_mul_f32 v[56:57], v[32:33], v[30:31]
	v_pk_mul_f32 v[30:31], v[60:61], v[36:37] op_sel_hi:[0,1]
	v_pk_mul_f32 v[58:59], v[62:63], v[30:31]
	v_bfe_u32 v1, v59, 16, 1
	v_bfe_u32 v5, v58, 16, 1
	v_add3_u32 v5, v58, v5, s66
	v_add3_u32 v1, v59, v1, s66
	v_bfe_u32 v61, v56, 16, 1
	v_bfe_u32 v62, v57, 16, 1
	v_add3_u32 v57, v57, v62, s66
	v_add3_u32 v56, v56, v61, s66
	v_lshrrev_b32_e32 v56, 16, v56
	v_lshrrev_b32_e32 v57, 16, v57
	v_and_or_b32 v59, v1, s63, v57
	v_and_or_b32 v58, v5, s63, v56
	v_cvt_pk_bf16_f32 v57, v27, v45
	v_cvt_pk_bf16_f32 v56, v26, v44
	ds_write_b128 v211, v[56:59]
	ds_write_b16 v212, v18 offset:36864
	ds_write_b16_d16_hi v212, v18 offset:37392
	ds_write_b16 v212, v19 offset:37920
	ds_write_b16_d16_hi v212, v19 offset:38448
	ds_write_b16 v212, v20 offset:38976
	ds_write_b16_d16_hi v212, v20 offset:39504
	ds_write_b16 v212, v21 offset:40032
	ds_write_b16_d16_hi v212, v21 offset:40560
	v_pk_mul_f32 v[18:19], v[60:61], v[66:67] op_sel_hi:[0,1]
	v_pk_mul_f32 v[26:27], v[74:75], v[18:19]
	v_pk_mul_f32 v[18:19], v[60:61], v[68:69] op_sel_hi:[0,1]
	v_pk_mul_f32 v[28:29], v[28:29], v[18:19]
	v_pk_mul_f32 v[18:19], v[60:61], v[70:71] op_sel_hi:[0,1]
	v_mov_b32_e32 v20, v22
	v_mov_b32_e32 v21, v24
	v_pk_mul_f32 v[44:45], v[20:21], v[18:19]
	v_pk_mul_f32 v[18:19], v[60:61], v[72:73] op_sel_hi:[0,1]
	v_mov_b32_e32 v24, v23
	v_pk_mul_f32 v[56:57], v[24:25], v[18:19]
	v_bfe_u32 v58, v29, 16, 1
	v_bfe_u32 v59, v28, 16, 1
	v_add3_u32 v59, v28, v59, s66
	v_add3_u32 v58, v29, v58, s66
	v_bfe_u32 v28, v26, 16, 1
	v_bfe_u32 v29, v27, 16, 1
	v_add3_u32 v27, v27, v29, s66
	v_add3_u32 v26, v26, v28, s66
	v_lshrrev_b32_e32 v26, 16, v26
	v_lshrrev_b32_e32 v27, 16, v27
	v_cvt_pk_bf16_f32 v29, v45, v57
	v_cvt_pk_bf16_f32 v28, v44, v56
	v_and_or_b32 v27, v58, s63, v27
	v_and_or_b32 v26, v59, s63, v26
	ds_write_b128 v211, v[26:29] offset:16
	ds_write_b16 v212, v14 offset:41088
	ds_write_b16_d16_hi v212, v14 offset:41616
	ds_write_b16 v212, v15 offset:42144
	ds_write_b16_d16_hi v212, v15 offset:42672
	ds_write_b16 v212, v16 offset:43200
	ds_write_b16_d16_hi v212, v16 offset:43728
	ds_write_b16 v212, v17 offset:44256
	ds_write_b16_d16_hi v212, v17 offset:44784
	v_pk_mul_f32 v[14:15], v[60:61], v[54:55] op_sel_hi:[0,1]
	v_pk_mul_f32 v[26:27], v[60:61], v[50:51] op_sel_hi:[0,1]
	s_addc_u32 s83, 0, s83
	v_mov_b32_e32 v3, v4
	v_mov_b32_e32 v2, s0
	v_lshl_add_u64 v[158:159], s[82:83], 0, v[158:159]
	v_mad_u64_u32 v[2:3], s[82:83], v158, s60, v[2:3]
	v_mad_i32_i24 v3, v159, s60, v3
	v_lshl_add_u64 v[202:203], v[196:197], 0, v[2:3]
	v_lshlrev_b64 v[2:3], 11, v[158:159]
	v_or_b32_e32 v2, s0, v2
	v_mov_b32_e32 v116, v4
	v_mov_b32_e32 v117, v4
	v_mov_b32_e32 v156, v4
	v_mov_b32_e32 v157, v4
	v_lshl_add_u64 v[204:205], v[198:199], 0, v[2:3]
	s_mov_b64 s[82:83], 0
	s_waitcnt vmcnt(3)
; #define LAS __attribute__((address_space(3)))
; __device__ __forceinline__ unsigned pk2(float lo, float hi) { return f2bf(lo) | (f2bf(hi) << 16); }
; __device__ __forceinline__ void attn_item(Frame& F, int item) {
;     ...
; #pragma unroll
;         for (int i = 0; i < 4; ++i) {
;             const f32x4 g0 = *(const f32x4*)(F.kg + half * 32 + 8 * i), g1 = *(const f32x4*)(F.kg + half * 32 + 8 * i + 4);
;             v4u o;
;             o.x = pk2(bflo(kw[i][0]) * rs * g0[0], bfhi(kw[i][0]) * rs * g0[1]); o.y = pk2(bflo(kw[i][1]) * rs * g0[2], bfhi(kw[i][1]) * rs * g0[3]);
;             o.z = pk2(bflo(kw[i][2]) * rs * g1[0], bfhi(kw[i][2]) * rs * g1[1]); o.w = pk2(bflo(kw[i][3]) * rs * g1[2], bfhi(kw[i][3]) * rs * g1[3]);
;             *(LAS v4u*)(Ks + key * KS_STRIDE + half * 32 + 8 * i) = o;
; #pragma unroll
;             for (int j = 0; j < 4; ++j) {
;                 Vt[(half * 32 + 8 * i + 2 * j) * VT2_STRIDE + key] = (bf16)(vw[i][j] & 0xffffu);
;                 Vt[(half * 32 + 8 * i + 2 * j + 1) * VT2_STRIDE + key] = (bf16)(vw[i][j] >> 16);
;             }
;         }
;     }
;     __syncthreads();
;     bf16x8 kf[9][2];
; #pragma unroll
;     for (int kt = 0; kt < 9; ++kt)
; #pragma unroll
;         for (int ks = 0; ks < 2; ++ks) kf[kt][ks] = *(const LAS bf16x8*)(Ks + (16 * w + 16 * kt + l15) * KS_STRIDE + 32 * ks + 8 * quad);
;     ...
;         for (int dt = 0; dt < 4; ++dt) {
;             f32x4 o = (f32x4){0.f, 0.f, 0.f, 0.f};
;             const LAS bf16* vrow = Vt + (16 * dt + l15) * VT2_STRIDE + 16 * w + 4 * quad;
; #pragma unroll
;             for (int kk = 0; kk < 5; ++kk) {
;                 const v2u lo = *(const LAS v2u*)(vrow + 32 * kk);
;                 v2u hi = (v2u){0u, 0u}; if (kk < 4) hi = *(const LAS v2u*)(vrow + 32 * kk + 16);
	v_mov_b32_e32 v30, v240
	v_mov_b32_e32 v31, v241
	v_mov_b32_e32 v32, v242
	v_mov_b32_e32 v33, v243
	v_mov_b32_e32 v28, v30
	s_waitcnt vmcnt(2)
	v_mov_b32_e32 v34, v244
	v_mov_b32_e32 v35, v245
	v_mov_b32_e32 v36, v246
	v_mov_b32_e32 v37, v247
	v_mov_b32_e32 v16, v34
	v_mov_b32_e32 v17, v36
	v_mov_b32_e32 v29, v32
	v_pk_mul_f32 v[14:15], v[14:15], v[16:17]
	v_pk_mul_f32 v[16:17], v[60:61], v[52:53] op_sel_hi:[0,1]
	v_mov_b32_e32 v36, v35
	v_pk_mul_f32 v[26:27], v[26:27], v[28:29]
	v_pk_mul_f32 v[28:29], v[60:61], v[48:49] op_sel_hi:[0,1]
	v_mov_b32_e32 v32, v31
	v_pk_mul_f32 v[16:17], v[16:17], v[36:37]
	v_pk_mul_f32 v[28:29], v[28:29], v[32:33]
	v_bfe_u32 v30, v17, 16, 1
	v_bfe_u32 v31, v16, 16, 1
	v_add3_u32 v31, v16, v31, s66
	v_add3_u32 v30, v17, v30, s66
	v_bfe_u32 v16, v14, 16, 1
	v_bfe_u32 v17, v15, 16, 1
	v_add3_u32 v15, v15, v17, s66
	v_add3_u32 v14, v14, v16, s66
	v_lshrrev_b32_e32 v14, 16, v14
	v_lshrrev_b32_e32 v15, 16, v15
	v_cvt_pk_bf16_f32 v17, v27, v29
	v_cvt_pk_bf16_f32 v16, v26, v28
	v_and_or_b32 v15, v30, s63, v15
	v_and_or_b32 v14, v31, s63, v14
	ds_write_b128 v211, v[14:17] offset:32
	ds_write_b16 v212, v10 offset:45312
	ds_write_b16_d16_hi v212, v10 offset:45840
	ds_write_b16 v212, v11 offset:46368
	ds_write_b16_d16_hi v212, v11 offset:46896
	ds_write_b16 v212, v12 offset:47424
	ds_write_b16_d16_hi v212, v12 offset:47952
	ds_write_b16 v212, v13 offset:48480
	ds_write_b16_d16_hi v212, v13 offset:49008
	v_pk_mul_f32 v[10:11], v[60:61], v[46:47] op_sel_hi:[0,1]
	s_waitcnt vmcnt(0)
	v_mov_b32_e32 v18, v248
	v_mov_b32_e32 v19, v249
	v_mov_b32_e32 v20, v250
	v_mov_b32_e32 v21, v251
	v_mov_b32_e32 v22, v252
	v_mov_b32_e32 v23, v253
	v_mov_b32_e32 v24, v254
	v_mov_b32_e32 v25, v255
	v_mov_b32_e32 v12, v22
	v_mov_b32_e32 v13, v24
	v_pk_mul_f32 v[14:15], v[60:61], v[40:41] op_sel_hi:[0,1]
	v_mov_b32_e32 v16, v18
	v_mov_b32_e32 v17, v20
	v_pk_mul_f32 v[10:11], v[10:11], v[12:13]
	v_pk_mul_f32 v[12:13], v[60:61], v[42:43] op_sel_hi:[0,1]
	v_mov_b32_e32 v24, v23
	v_pk_mul_f32 v[14:15], v[14:15], v[16:17]
	v_pk_mul_f32 v[16:17], v[60:61], v[38:39] op_sel_hi:[0,1]
	v_mov_b32_e32 v20, v19
	v_pk_mul_f32 v[12:13], v[12:13], v[24:25]
	v_pk_mul_f32 v[16:17], v[16:17], v[20:21]
	v_bfe_u32 v18, v13, 16, 1
	v_bfe_u32 v19, v12, 16, 1
	v_add3_u32 v19, v12, v19, s66
	v_add3_u32 v18, v13, v18, s66
	v_bfe_u32 v12, v10, 16, 1
	v_bfe_u32 v13, v11, 16, 1
	v_add3_u32 v11, v11, v13, s66
	v_add3_u32 v10, v10, v12, s66
	v_lshrrev_b32_e32 v10, 16, v10
	v_lshrrev_b32_e32 v11, 16, v11
	v_cvt_pk_bf16_f32 v13, v15, v17
	v_cvt_pk_bf16_f32 v12, v14, v16
	v_and_or_b32 v11, v18, s63, v11
	v_and_or_b32 v10, v19, s63, v10
	ds_write_b128 v211, v[10:13] offset:48
	ds_write_b16 v212, v6 offset:49536
	ds_write_b16_d16_hi v212, v6 offset:50064
	ds_write_b16 v212, v7 offset:50592
	ds_write_b16_d16_hi v212, v7 offset:51120
	ds_write_b16 v212, v8 offset:51648
	ds_write_b16_d16_hi v212, v8 offset:52176
	ds_write_b16 v212, v9 offset:52704
	ds_write_b16_d16_hi v212, v9 offset:53232
	s_waitcnt lgkmcnt(0)
	s_barrier
	ds_read_b128 v[6:9], v214
	ds_read_b128 v[10:13], v214 offset:64
	ds_read_b128 v[14:17], v215
	ds_read_b128 v[18:21], v215 offset:64
	ds_read_b128 v[22:25], v216
	ds_read_b128 v[26:29], v216 offset:64
	ds_read_b128 v[30:33], v217
	ds_read_b128 v[34:37], v217 offset:64
	ds_read_b128 v[38:41], v218
	ds_read_b128 v[42:45], v218 offset:64
	ds_read_b128 v[46:49], v219
	ds_read_b128 v[50:53], v219 offset:64
	ds_read_b128 v[54:57], v220
	ds_read_b128 v[58:61], v220 offset:64
	ds_read_b128 v[62:65], v221
	ds_read_b128 v[66:69], v221 offset:64
	ds_read_b128 v[70:73], v222
	ds_read_b128 v[74:77], v222 offset:64
	v_add_u32_e32 v1, 0x9000, v223
	v_add_u32_e32 v5, 0x100, v223
	ds_read2st64_b64 v[96:99], v5 offset0:72 offset1:88
	ds_read2_b64 v[78:81], v1 offset1:4
	ds_read2_b64 v[82:85], v1 offset0:8 offset1:12
	ds_read2_b64 v[86:89], v1 offset0:16 offset1:20
	ds_read2_b64 v[90:93], v1 offset0:24 offset1:28
	v_add_u32_e32 v1, 0xb000, v223
	ds_read2_b64 v[100:103], v1 offset0:36 offset1:40
	ds_read2_b64 v[104:107], v1 offset0:44 offset1:48
	ds_read2_b64 v[108:111], v1 offset0:52 offset1:56
	ds_read2_b64 v[112:115], v1 offset0:60 offset1:64
	v_add_u32_e32 v1, 0xd000, v223
	ds_read2st64_b64 v[136:139], v5 offset0:105 offset1:121
	ds_read2_b64 v[118:121], v1 offset0:64 offset1:68
	ds_read2_b64 v[122:125], v1 offset0:72 offset1:76
	ds_read2_b64 v[126:129], v1 offset0:80 offset1:84
	ds_read2_b64 v[130:133], v1 offset0:88 offset1:92
	v_add_u32_e32 v1, 0xf000, v223
	ds_read2_b64 v[140:143], v1 offset0:100 offset1:104
	ds_read2_b64 v[144:147], v1 offset0:108 offset1:112
	ds_read2_b64 v[148:151], v1 offset0:116 offset1:120
	ds_read2_b64 v[152:155], v1 offset0:124 offset1:128
	s_waitcnt lgkmcnt(14)
	v_mov_b32_e32 v94, v96
	v_mov_b32_e32 v95, v97
	v_mov_b32_e32 v96, v4
	v_mov_b32_e32 v97, v4
	s_waitcnt lgkmcnt(8)
	v_mov_b32_e32 v134, v136
	v_mov_b32_e32 v135, v137
	v_mov_b32_e32 v136, v4
	v_mov_b32_e32 v137, v4
	s_branch .LBB0_490
